# P5 epilogue de-serialised: the 8 per-row rmsnorm scalars are computed up front with all loads in flight (one quarter-row per fq lane + 2 bpermutes) instead of 8 dependent load-wait groups
# speedup vs baseline: 1.0236x; 1.0090x over previous
; __device__ __forceinline__ float sigmoidf_(float x) { return __builtin_amdgcn_rcpf(1.0f + __builtin_amdgcn_exp2f(-x * LOG2E)); }
; __device__ __forceinline__ unsigned cvt_pk_bf16(float lo, float hi) { unsigned r; asm volatile("v_cvt_pk_bf16_f32 %0, %1, %2" : "=v"(r) : "v"(lo), "v"(hi)); return r; }
; __device__ __forceinline__ float row_rs(const float* ss, int row) {
;     const f32x4* sp = (const f32x4*)(ss + (size_t)row * 16);
;     const f32x4 a = sp[0], b = sp[1], c = sp[2], d = sp[3];
;     const float tot = ((a[0] + a[1]) + (a[2] + a[3])) + ((b[0] + b[1]) + (b[2] + b[3])) + ((c[0] + c[1]) + (c[2] + c[3])) + ((d[0] + d[1]) + (d[2] + d[3]));
;     return __builtin_amdgcn_rsqf(tot * (1.0f / 1024.0f) + EPSN);
; }
;     __device__ __forceinline__ void operator()(const f32x4 (&acc)[2][2][4][2], const Unit& u, int wr, int wc, int fr, int fq) const {
;     ...
;         for (int ai = 0; ai < 2; ++ai)
; #pragma unroll
;             for (int m = 0; m < 4; ++m) {
;                 const int row = u.pm * BM + ai * HALF + wr * 64 + m * 16 + fr;
;                 const float rs = row_rs(ss, row);
;                 float a[8];
; #pragma unroll
;                 for (int n = 0; n < 2; ++n)
; #pragma unroll
;                     for (int j = 0; j < 4; ++j) { const float gt = rs * acc[ai][0][m][n][j], up = rs * acc[ai][1][m][n][j]; a[4 * n + j] = gt * sigmoidf_(gt) * up; }
;                 u32x4 w; w.x = cvt_pk_bf16(a[0], a[1]); w.y = cvt_pk_bf16(a[2], a[3]); w.z = cvt_pk_bf16(a[4], a[5]); w.w = cvt_pk_bf16(a[6], a[7]);
;                 *(u32x4*)(ACT + (size_t)row * DFF + u.pn * HALF + wc * 32 + fq * 8) = w;
.LBB0_1120:
	v_lshl_add_u32 v146, s25, 8, v151
	v_and_b32_e32 v212, 63, v251
	v_lshrrev_b32_e32 v213, 4, v212
	v_lshlrev_b32_e32 v213, 4, v213
	v_xor_b32_e32 v214, 16, v212
	v_lshlrev_b32_e32 v214, 2, v214
	v_xor_b32_e32 v215, 32, v212
	v_lshlrev_b32_e32 v215, 2, v215
	v_add_u32_e32 v216, 0x0, v146
	v_lshlrev_b32_e32 v216, 6, v216
	v_add_u32_e32 v216, v216, v213
	global_load_dwordx4 v[172:175], v216, s[2:3]
	v_add_u32_e32 v216, 0x10, v146
	v_lshlrev_b32_e32 v216, 6, v216
	v_add_u32_e32 v216, v216, v213
	global_load_dwordx4 v[176:179], v216, s[2:3]
	v_add_u32_e32 v216, 0x20, v146
	v_lshlrev_b32_e32 v216, 6, v216
	v_add_u32_e32 v216, v216, v213
	global_load_dwordx4 v[180:183], v216, s[2:3]
	v_add_u32_e32 v216, 0x30, v146
	v_lshlrev_b32_e32 v216, 6, v216
	v_add_u32_e32 v216, v216, v213
	global_load_dwordx4 v[184:187], v216, s[2:3]
	v_add_u32_e32 v216, 0x80, v146
	v_lshlrev_b32_e32 v216, 6, v216
	v_add_u32_e32 v216, v216, v213
	global_load_dwordx4 v[188:191], v216, s[2:3]
	v_add_u32_e32 v216, 0x90, v146
	v_lshlrev_b32_e32 v216, 6, v216
	v_add_u32_e32 v216, v216, v213
	global_load_dwordx4 v[192:195], v216, s[2:3]
	v_add_u32_e32 v216, 0xa0, v146
	v_lshlrev_b32_e32 v216, 6, v216
	v_add_u32_e32 v216, v216, v213
	global_load_dwordx4 v[196:199], v216, s[2:3]
	v_add_u32_e32 v216, 0xb0, v146
	v_lshlrev_b32_e32 v216, 6, v216
	v_add_u32_e32 v216, v216, v213
	global_load_dwordx4 v[200:203], v216, s[2:3]
	s_waitcnt vmcnt(0)
	v_add_f32_e32 v172, v172, v173
	v_add_f32_e32 v174, v174, v175
	v_add_f32_e32 v172, v172, v174
	v_add_f32_e32 v176, v176, v177
	v_add_f32_e32 v178, v178, v179
	v_add_f32_e32 v176, v176, v178
	v_add_f32_e32 v180, v180, v181
	v_add_f32_e32 v182, v182, v183
	v_add_f32_e32 v180, v180, v182
	v_add_f32_e32 v184, v184, v185
	v_add_f32_e32 v186, v186, v187
	v_add_f32_e32 v184, v184, v186
	v_add_f32_e32 v188, v188, v189
	v_add_f32_e32 v190, v190, v191
	v_add_f32_e32 v188, v188, v190
	v_add_f32_e32 v192, v192, v193
	v_add_f32_e32 v194, v194, v195
	v_add_f32_e32 v192, v192, v194
	v_add_f32_e32 v196, v196, v197
	v_add_f32_e32 v198, v198, v199
	v_add_f32_e32 v196, v196, v198
	v_add_f32_e32 v200, v200, v201
	v_add_f32_e32 v202, v202, v203
	v_add_f32_e32 v200, v200, v202
	ds_bpermute_b32 v173, v214, v172
	ds_bpermute_b32 v177, v214, v176
	ds_bpermute_b32 v181, v214, v180
	ds_bpermute_b32 v185, v214, v184
	ds_bpermute_b32 v189, v214, v188
	ds_bpermute_b32 v193, v214, v192
	ds_bpermute_b32 v197, v214, v196
	ds_bpermute_b32 v201, v214, v200
	s_waitcnt lgkmcnt(0)
	v_add_f32_e32 v172, v172, v173
	v_add_f32_e32 v176, v176, v177
	v_add_f32_e32 v180, v180, v181
	v_add_f32_e32 v184, v184, v185
	v_add_f32_e32 v188, v188, v189
	v_add_f32_e32 v192, v192, v193
	v_add_f32_e32 v196, v196, v197
	v_add_f32_e32 v200, v200, v201
	ds_bpermute_b32 v173, v215, v172
	ds_bpermute_b32 v177, v215, v176
	ds_bpermute_b32 v181, v215, v180
	ds_bpermute_b32 v185, v215, v184
	ds_bpermute_b32 v189, v215, v188
	ds_bpermute_b32 v193, v215, v192
	ds_bpermute_b32 v197, v215, v196
	ds_bpermute_b32 v201, v215, v200
	s_waitcnt lgkmcnt(0)
	v_add_f32_e32 v172, v172, v173
	v_fmamk_f32 v172, v172, 0x3a800000, v149
	v_rsq_f32_e32 v204, v172
	v_add_f32_e32 v176, v176, v177
	v_fmamk_f32 v176, v176, 0x3a800000, v149
	v_rsq_f32_e32 v205, v176
	v_add_f32_e32 v180, v180, v181
	v_fmamk_f32 v180, v180, 0x3a800000, v149
	v_rsq_f32_e32 v206, v180
	v_add_f32_e32 v184, v184, v185
	v_fmamk_f32 v184, v184, 0x3a800000, v149
	v_rsq_f32_e32 v207, v184
	v_add_f32_e32 v188, v188, v189
	v_fmamk_f32 v188, v188, 0x3a800000, v149
	v_rsq_f32_e32 v208, v188
	v_add_f32_e32 v192, v192, v193
	v_fmamk_f32 v192, v192, 0x3a800000, v149
	v_rsq_f32_e32 v209, v192
	v_add_f32_e32 v196, v196, v197
	v_fmamk_f32 v196, v196, 0x3a800000, v149
	v_rsq_f32_e32 v210, v196
	v_add_f32_e32 v200, v200, v201
	v_fmamk_f32 v200, v200, 0x3a800000, v149
	v_rsq_f32_e32 v211, v200
	v_ashrrev_i32_e32 v147, 31, v146
	v_lshlrev_b64 v[154:155], 6, v[146:147]
	v_lshl_add_u64 v[166:167], s[2:3], 0, v[154:155]
	s_nop 0
	s_lshl_b32 vcc_lo, s24, 7
	s_ashr_i32 vcc_hi, vcc_lo, 31
	s_lshl_b64 vcc, vcc, 1
	s_nop 0
	s_nop 0
	v_mov_b32_e32 v148, v204
	v_mov_b32_e32 v154, v120
	v_mov_b32_e32 v155, v124
	v_mov_b32_e32 v124, v121
	v_pk_mul_f32 v[154:155], v[154:155], v[148:149] op_sel_hi:[1,0]
	s_nop 0
	v_mul_f32_e32 v120, 0xbfb8aa3b, v155
	v_exp_f32_e32 v120, v120
	s_nop 0
	v_add_f32_e32 v120, 1.0, v120
	v_rcp_f32_e32 v120, v120
	s_nop 0
	v_mul_f32_e32 v120, v155, v120
	v_mul_f32_e32 v147, v154, v120
	v_pk_mul_f32 v[120:121], v[124:125], v[148:149] op_sel_hi:[1,0]
	s_nop 0
	v_mul_f32_e32 v124, 0xbfb8aa3b, v121
	v_exp_f32_e32 v124, v124
	s_nop 0
	v_add_f32_e32 v124, 1.0, v124
	v_rcp_f32_e32 v124, v124
	s_nop 0
	v_mul_f32_e32 v121, v121, v124
	v_mul_f32_e32 v124, v120, v121
	v_mov_b32_e32 v120, v122
	v_mov_b32_e32 v121, v126
	v_pk_mul_f32 v[120:121], v[120:121], v[148:149] op_sel_hi:[1,0]
	v_mov_b32_e32 v126, v123
	v_mul_f32_e32 v122, 0xbfb8aa3b, v121
	v_exp_f32_e32 v122, v122
	s_nop 0
	v_add_f32_e32 v122, 1.0, v122
	v_rcp_f32_e32 v122, v122
	s_nop 0
	v_mul_f32_e32 v121, v121, v122
	v_mul_f32_e32 v122, v120, v121
	v_pk_mul_f32 v[120:121], v[126:127], v[148:149] op_sel_hi:[1,0]
	s_nop 0
	v_mul_f32_e32 v123, 0xbfb8aa3b, v121
	v_exp_f32_e32 v123, v123
	s_nop 0
	v_add_f32_e32 v123, 1.0, v123
	v_rcp_f32_e32 v123, v123
	s_nop 0
	v_mul_f32_e32 v121, v121, v123
	v_mul_f32_e32 v123, v120, v121
	v_mov_b32_e32 v120, v112
	v_mov_b32_e32 v121, v116
	v_pk_mul_f32 v[120:121], v[120:121], v[148:149] op_sel_hi:[1,0]
	v_mov_b32_e32 v116, v113
	v_mul_f32_e32 v112, 0xbfb8aa3b, v121
	v_exp_f32_e32 v112, v112
	s_nop 0
	v_add_f32_e32 v112, 1.0, v112
	v_rcp_f32_e32 v112, v112
	s_nop 0
; __device__ __forceinline__ float sigmoidf_(float x) { return __builtin_amdgcn_rcpf(1.0f + __builtin_amdgcn_exp2f(-x * LOG2E)); }
; __device__ __forceinline__ unsigned cvt_pk_bf16(float lo, float hi) { unsigned r; asm volatile("v_cvt_pk_bf16_f32 %0, %1, %2" : "=v"(r) : "v"(lo), "v"(hi)); return r; }
;     __device__ __forceinline__ void operator()(const f32x4 (&acc)[2][2][4][2], const Unit& u, int wr, int wc, int fr, int fq) const {
;     ...
;         for (int ai = 0; ai < 2; ++ai)
; #pragma unroll
;             for (int m = 0; m < 4; ++m) {
;                 const int row = u.pm * BM + ai * HALF + wr * 64 + m * 16 + fr;
;                 const float rs = row_rs(ss, row);
;                 float a[8];
; #pragma unroll
;                 for (int n = 0; n < 2; ++n)
; #pragma unroll
;                     for (int j = 0; j < 4; ++j) { const float gt = rs * acc[ai][0][m][n][j], up = rs * acc[ai][1][m][n][j]; a[4 * n + j] = gt * sigmoidf_(gt) * up; }
;                 u32x4 w; w.x = cvt_pk_bf16(a[0], a[1]); w.y = cvt_pk_bf16(a[2], a[3]); w.z = cvt_pk_bf16(a[4], a[5]); w.w = cvt_pk_bf16(a[6], a[7]);
;                 *(u32x4*)(ACT + (size_t)row * DFF + u.pn * HALF + wc * 32 + fq * 8) = w;
	v_mul_f32_e32 v112, v121, v112
	v_mul_f32_e32 v120, v120, v112
	v_pk_mul_f32 v[112:113], v[116:117], v[148:149] op_sel_hi:[1,0]
	s_nop 0
	v_mul_f32_e32 v116, 0xbfb8aa3b, v113
	v_exp_f32_e32 v116, v116
	s_nop 0
	v_add_f32_e32 v116, 1.0, v116
	v_rcp_f32_e32 v116, v116
	s_nop 0
	v_mul_f32_e32 v113, v113, v116
	v_mul_f32_e32 v116, v112, v113
	v_mov_b32_e32 v112, v114
	v_mov_b32_e32 v113, v118
	v_pk_mul_f32 v[112:113], v[112:113], v[148:149] op_sel_hi:[1,0]
	v_mov_b32_e32 v118, v115
	v_mul_f32_e32 v114, 0xbfb8aa3b, v113
	v_exp_f32_e32 v114, v114
	s_nop 0
	v_add_f32_e32 v114, 1.0, v114
	v_rcp_f32_e32 v114, v114
	s_nop 0
	v_mul_f32_e32 v113, v113, v114
	v_mul_f32_e32 v117, v112, v113
	v_pk_mul_f32 v[112:113], v[118:119], v[148:149] op_sel_hi:[1,0]
	s_nop 0
	v_mul_f32_e32 v114, 0xbfb8aa3b, v113
	v_exp_f32_e32 v114, v114
	s_nop 0
	v_add_f32_e32 v114, 1.0, v114
	v_rcp_f32_e32 v114, v114
	s_nop 0
	v_mul_f32_e32 v113, v113, v114
	v_mul_f32_e32 v115, v112, v113
	v_cvt_pk_bf16_f32 v112, v147, v124
	v_cvt_pk_bf16_f32 v113, v122, v123
	v_cvt_pk_bf16_f32 v114, v120, v116
	v_cvt_pk_bf16_f32 v115, v117, v115
	v_mov_b64_e32 v[116:117], s[34:35]
	v_mad_i64_i32 v[118:119], s[4:5], v146, s40, v[116:117]
	v_lshl_add_u64 v[118:119], v[118:119], 0, vcc
	v_lshl_add_u64 v[118:119], v[118:119], 0, s[86:87]
	v_lshl_add_u64 v[118:119], v[118:119], 0, v[128:129]
	global_store_dwordx4 v[118:119], v[112:115], off
	s_nop 1
	v_or_b32_e32 v112, 16, v146
	v_ashrrev_i32_e32 v113, 31, v112
	v_lshlrev_b64 v[114:115], 6, v[112:113]
	v_lshl_add_u64 v[114:115], s[2:3], 0, v[114:115]
	s_nop 0
	v_mov_b32_e32 v118, v104
	v_mov_b32_e32 v114, v205
	v_mov_b32_e32 v119, v108
	v_mov_b32_e32 v108, v105
	v_pk_mul_f32 v[118:119], v[118:119], v[114:115] op_sel_hi:[1,0]
	s_nop 0
	v_mul_f32_e32 v104, 0xbfb8aa3b, v119
	v_exp_f32_e32 v104, v104
	s_nop 0
	v_add_f32_e32 v104, 1.0, v104
	v_rcp_f32_e32 v104, v104
	s_nop 0
	v_mul_f32_e32 v104, v119, v104
	v_mul_f32_e32 v113, v118, v104
	v_pk_mul_f32 v[104:105], v[108:109], v[114:115] op_sel_hi:[1,0]
	s_nop 0
	v_mul_f32_e32 v108, 0xbfb8aa3b, v105
	v_exp_f32_e32 v108, v108
	s_nop 0
	v_add_f32_e32 v108, 1.0, v108
	v_rcp_f32_e32 v108, v108
	s_nop 0
	v_mul_f32_e32 v105, v105, v108
	v_mul_f32_e32 v108, v104, v105
	v_mov_b32_e32 v104, v106
	v_mov_b32_e32 v105, v110
	v_pk_mul_f32 v[104:105], v[104:105], v[114:115] op_sel_hi:[1,0]
	v_mov_b32_e32 v110, v107
	v_mul_f32_e32 v106, 0xbfb8aa3b, v105
	v_exp_f32_e32 v106, v106
	s_nop 0
	v_add_f32_e32 v106, 1.0, v106
	v_rcp_f32_e32 v106, v106
	s_nop 0
	v_mul_f32_e32 v105, v105, v106
	v_mul_f32_e32 v106, v104, v105
	v_pk_mul_f32 v[104:105], v[110:111], v[114:115] op_sel_hi:[1,0]
	s_nop 0
	v_mul_f32_e32 v107, 0xbfb8aa3b, v105
	v_exp_f32_e32 v107, v107
	s_nop 0
	v_add_f32_e32 v107, 1.0, v107
	v_rcp_f32_e32 v107, v107
	s_nop 0
	v_mul_f32_e32 v105, v105, v107
	v_mul_f32_e32 v107, v104, v105
	v_mov_b32_e32 v104, v96
	v_mov_b32_e32 v105, v100
	v_pk_mul_f32 v[104:105], v[104:105], v[114:115] op_sel_hi:[1,0]
	v_mov_b32_e32 v100, v97
	v_mul_f32_e32 v96, 0xbfb8aa3b, v105
	v_exp_f32_e32 v96, v96
	s_nop 0
	v_add_f32_e32 v96, 1.0, v96
	v_rcp_f32_e32 v96, v96
	s_nop 0
	v_mul_f32_e32 v96, v105, v96
	v_mul_f32_e32 v104, v104, v96
	v_pk_mul_f32 v[96:97], v[100:101], v[114:115] op_sel_hi:[1,0]
	s_nop 0
	v_mul_f32_e32 v100, 0xbfb8aa3b, v97
	v_exp_f32_e32 v100, v100
	s_nop 0
	v_add_f32_e32 v100, 1.0, v100
	v_rcp_f32_e32 v100, v100
	s_nop 0
	v_mul_f32_e32 v97, v97, v100
	v_mul_f32_e32 v100, v96, v97
	v_mov_b32_e32 v96, v98
	v_mov_b32_e32 v97, v102
	v_pk_mul_f32 v[96:97], v[96:97], v[114:115] op_sel_hi:[1,0]
	v_mov_b32_e32 v102, v99
	v_mul_f32_e32 v98, 0xbfb8aa3b, v97
	v_exp_f32_e32 v98, v98
	s_nop 0
	v_add_f32_e32 v98, 1.0, v98
	v_rcp_f32_e32 v98, v98
	s_nop 0
	v_mul_f32_e32 v97, v97, v98
	v_mul_f32_e32 v101, v96, v97
	v_pk_mul_f32 v[96:97], v[102:103], v[114:115] op_sel_hi:[1,0]
	s_nop 0
	v_mul_f32_e32 v98, 0xbfb8aa3b, v97
	v_exp_f32_e32 v98, v98
	s_nop 0
	v_add_f32_e32 v98, 1.0, v98
	v_rcp_f32_e32 v98, v98
	s_nop 0
	v_mul_f32_e32 v97, v97, v98
	v_mul_f32_e32 v99, v96, v97
	v_cvt_pk_bf16_f32 v96, v113, v108
	v_cvt_pk_bf16_f32 v97, v106, v107
	v_cvt_pk_bf16_f32 v98, v104, v100
	v_cvt_pk_bf16_f32 v99, v101, v99
	v_mad_i64_i32 v[100:101], s[4:5], v112, s40, v[116:117]
	v_lshl_add_u64 v[100:101], v[100:101], 0, vcc
	v_lshl_add_u64 v[100:101], v[100:101], 0, s[86:87]
	v_lshl_add_u64 v[100:101], v[100:101], 0, v[128:129]
	global_store_dwordx4 v[100:101], v[96:99], off
	s_nop 1
	v_or_b32_e32 v96, 32, v146
	v_ashrrev_i32_e32 v97, 31, v96
	v_lshlrev_b64 v[98:99], 6, v[96:97]
	v_lshl_add_u64 v[110:111], s[2:3], 0, v[98:99]
	s_nop 0
	s_nop 0
	v_mov_b32_e32 v100, v88
	v_mov_b32_e32 v98, v206
	v_mov_b32_e32 v101, v92
	v_mov_b32_e32 v92, v89
	v_pk_mul_f32 v[100:101], v[100:101], v[98:99] op_sel_hi:[1,0]
	s_nop 0
	v_mul_f32_e32 v88, 0xbfb8aa3b, v101
	v_exp_f32_e32 v88, v88
	s_nop 0
	v_add_f32_e32 v88, 1.0, v88
	v_rcp_f32_e32 v88, v88
	s_nop 0
	v_mul_f32_e32 v88, v101, v88
	v_mul_f32_e32 v97, v100, v88
	v_pk_mul_f32 v[88:89], v[92:93], v[98:99] op_sel_hi:[1,0]
	s_nop 0
	v_mul_f32_e32 v92, 0xbfb8aa3b, v89
	v_exp_f32_e32 v92, v92
	s_nop 0
	v_add_f32_e32 v92, 1.0, v92
	v_rcp_f32_e32 v92, v92
	s_nop 0
	v_mul_f32_e32 v89, v89, v92
	v_mul_f32_e32 v92, v88, v89
	v_mov_b32_e32 v88, v90
	v_mov_b32_e32 v89, v94
	v_pk_mul_f32 v[88:89], v[88:89], v[98:99] op_sel_hi:[1,0]
	v_mov_b32_e32 v94, v91
	v_mul_f32_e32 v90, 0xbfb8aa3b, v89
	v_exp_f32_e32 v90, v90
	s_nop 0
	v_add_f32_e32 v90, 1.0, v90
	v_rcp_f32_e32 v90, v90
	s_nop 0
	v_mul_f32_e32 v89, v89, v90
	v_mul_f32_e32 v90, v88, v89
	v_pk_mul_f32 v[88:89], v[94:95], v[98:99] op_sel_hi:[1,0]
	s_nop 0
; __device__ __forceinline__ float sigmoidf_(float x) { return __builtin_amdgcn_rcpf(1.0f + __builtin_amdgcn_exp2f(-x * LOG2E)); }
; __device__ __forceinline__ unsigned cvt_pk_bf16(float lo, float hi) { unsigned r; asm volatile("v_cvt_pk_bf16_f32 %0, %1, %2" : "=v"(r) : "v"(lo), "v"(hi)); return r; }
;     __device__ __forceinline__ void operator()(const f32x4 (&acc)[2][2][4][2], const Unit& u, int wr, int wc, int fr, int fq) const {
;     ...
;         for (int ai = 0; ai < 2; ++ai)
; #pragma unroll
;             for (int m = 0; m < 4; ++m) {
;                 const int row = u.pm * BM + ai * HALF + wr * 64 + m * 16 + fr;
;                 const float rs = row_rs(ss, row);
;                 float a[8];
; #pragma unroll
;                 for (int n = 0; n < 2; ++n)
; #pragma unroll
;                     for (int j = 0; j < 4; ++j) { const float gt = rs * acc[ai][0][m][n][j], up = rs * acc[ai][1][m][n][j]; a[4 * n + j] = gt * sigmoidf_(gt) * up; }
;                 u32x4 w; w.x = cvt_pk_bf16(a[0], a[1]); w.y = cvt_pk_bf16(a[2], a[3]); w.z = cvt_pk_bf16(a[4], a[5]); w.w = cvt_pk_bf16(a[6], a[7]);
;                 *(u32x4*)(ACT + (size_t)row * DFF + u.pn * HALF + wc * 32 + fq * 8) = w;
	v_mul_f32_e32 v91, 0xbfb8aa3b, v89
	v_exp_f32_e32 v91, v91
	s_nop 0
	v_add_f32_e32 v91, 1.0, v91
	v_rcp_f32_e32 v91, v91
	s_nop 0
	v_mul_f32_e32 v89, v89, v91
	v_mul_f32_e32 v91, v88, v89
	v_mov_b32_e32 v88, v80
	v_mov_b32_e32 v89, v84
	v_pk_mul_f32 v[88:89], v[88:89], v[98:99] op_sel_hi:[1,0]
	v_mov_b32_e32 v84, v81
	v_mul_f32_e32 v80, 0xbfb8aa3b, v89
	v_exp_f32_e32 v80, v80
	s_nop 0
	v_add_f32_e32 v80, 1.0, v80
	v_rcp_f32_e32 v80, v80
	s_nop 0
	v_mul_f32_e32 v80, v89, v80
	v_mul_f32_e32 v88, v88, v80
	v_pk_mul_f32 v[80:81], v[84:85], v[98:99] op_sel_hi:[1,0]
	s_nop 0
	v_mul_f32_e32 v84, 0xbfb8aa3b, v81
	v_exp_f32_e32 v84, v84
	s_nop 0
	v_add_f32_e32 v84, 1.0, v84
	v_rcp_f32_e32 v84, v84
	s_nop 0
	v_mul_f32_e32 v81, v81, v84
	v_mul_f32_e32 v84, v80, v81
	v_mov_b32_e32 v80, v82
	v_mov_b32_e32 v81, v86
	v_pk_mul_f32 v[80:81], v[80:81], v[98:99] op_sel_hi:[1,0]
	v_mov_b32_e32 v86, v83
	v_mul_f32_e32 v82, 0xbfb8aa3b, v81
	v_exp_f32_e32 v82, v82
	s_nop 0
	v_add_f32_e32 v82, 1.0, v82
	v_rcp_f32_e32 v82, v82
	s_nop 0
	v_mul_f32_e32 v81, v81, v82
	v_mul_f32_e32 v85, v80, v81
	v_pk_mul_f32 v[80:81], v[86:87], v[98:99] op_sel_hi:[1,0]
	s_nop 0
	v_mul_f32_e32 v82, 0xbfb8aa3b, v81
	v_exp_f32_e32 v82, v82
	s_nop 0
	v_add_f32_e32 v82, 1.0, v82
	v_rcp_f32_e32 v82, v82
	s_nop 0
	v_mul_f32_e32 v81, v81, v82
	v_mul_f32_e32 v83, v80, v81
	v_cvt_pk_bf16_f32 v80, v97, v92
	v_cvt_pk_bf16_f32 v81, v90, v91
	v_cvt_pk_bf16_f32 v82, v88, v84
	v_cvt_pk_bf16_f32 v83, v85, v83
	v_mad_i64_i32 v[84:85], s[4:5], v96, s40, v[116:117]
	v_lshl_add_u64 v[84:85], v[84:85], 0, vcc
	v_lshl_add_u64 v[84:85], v[84:85], 0, s[86:87]
	v_lshl_add_u64 v[84:85], v[84:85], 0, v[128:129]
	global_store_dwordx4 v[84:85], v[80:83], off
	s_nop 1
	v_or_b32_e32 v80, 48, v146
	v_ashrrev_i32_e32 v81, 31, v80
	v_lshlrev_b64 v[82:83], 6, v[80:81]
	v_lshl_add_u64 v[94:95], s[2:3], 0, v[82:83]
	s_nop 0
	s_nop 0
	v_mov_b32_e32 v84, v72
	v_mov_b32_e32 v82, v207
	v_mov_b32_e32 v85, v76
	v_mov_b32_e32 v76, v73
	v_pk_mul_f32 v[84:85], v[84:85], v[82:83] op_sel_hi:[1,0]
	s_nop 0
	v_mul_f32_e32 v72, 0xbfb8aa3b, v85
	v_exp_f32_e32 v72, v72
	s_nop 0
	v_add_f32_e32 v72, 1.0, v72
	v_rcp_f32_e32 v72, v72
	s_nop 0
	v_mul_f32_e32 v72, v85, v72
	v_mul_f32_e32 v81, v84, v72
	v_pk_mul_f32 v[72:73], v[76:77], v[82:83] op_sel_hi:[1,0]
	s_nop 0
	v_mul_f32_e32 v76, 0xbfb8aa3b, v73
	v_exp_f32_e32 v76, v76
	s_nop 0
	v_add_f32_e32 v76, 1.0, v76
	v_rcp_f32_e32 v76, v76
	s_nop 0
	v_mul_f32_e32 v73, v73, v76
	v_mul_f32_e32 v76, v72, v73
	v_mov_b32_e32 v72, v74
	v_mov_b32_e32 v73, v78
	v_pk_mul_f32 v[72:73], v[72:73], v[82:83] op_sel_hi:[1,0]
	v_mov_b32_e32 v78, v75
	v_mul_f32_e32 v74, 0xbfb8aa3b, v73
	v_exp_f32_e32 v74, v74
	s_nop 0
	v_add_f32_e32 v74, 1.0, v74
	v_rcp_f32_e32 v74, v74
	s_nop 0
	v_mul_f32_e32 v73, v73, v74
	v_mul_f32_e32 v74, v72, v73
	v_pk_mul_f32 v[72:73], v[78:79], v[82:83] op_sel_hi:[1,0]
	s_nop 0
	v_mul_f32_e32 v75, 0xbfb8aa3b, v73
	v_exp_f32_e32 v75, v75
	s_nop 0
	v_add_f32_e32 v75, 1.0, v75
	v_rcp_f32_e32 v75, v75
	s_nop 0
	v_mul_f32_e32 v73, v73, v75
	v_mul_f32_e32 v75, v72, v73
	v_mov_b32_e32 v72, v64
	v_mov_b32_e32 v73, v68
	v_pk_mul_f32 v[72:73], v[72:73], v[82:83] op_sel_hi:[1,0]
	v_mov_b32_e32 v68, v65
	v_mul_f32_e32 v64, 0xbfb8aa3b, v73
	v_exp_f32_e32 v64, v64
	s_nop 0
	v_add_f32_e32 v64, 1.0, v64
	v_rcp_f32_e32 v64, v64
	s_nop 0
	v_mul_f32_e32 v64, v73, v64
	v_mul_f32_e32 v72, v72, v64
	v_pk_mul_f32 v[64:65], v[68:69], v[82:83] op_sel_hi:[1,0]
	s_nop 0
	v_mul_f32_e32 v68, 0xbfb8aa3b, v65
	v_exp_f32_e32 v68, v68
	s_nop 0
	v_add_f32_e32 v68, 1.0, v68
	v_rcp_f32_e32 v68, v68
	s_nop 0
	v_mul_f32_e32 v65, v65, v68
	v_mul_f32_e32 v68, v64, v65
	v_mov_b32_e32 v64, v66
	v_mov_b32_e32 v65, v70
	v_pk_mul_f32 v[64:65], v[64:65], v[82:83] op_sel_hi:[1,0]
	v_mov_b32_e32 v70, v67
	v_mul_f32_e32 v66, 0xbfb8aa3b, v65
	v_exp_f32_e32 v66, v66
	s_nop 0
	v_add_f32_e32 v66, 1.0, v66
	v_rcp_f32_e32 v66, v66
	s_nop 0
	v_mul_f32_e32 v65, v65, v66
	v_mul_f32_e32 v69, v64, v65
	v_pk_mul_f32 v[64:65], v[70:71], v[82:83] op_sel_hi:[1,0]
	s_nop 0
	v_mul_f32_e32 v66, 0xbfb8aa3b, v65
	v_exp_f32_e32 v66, v66
	s_nop 0
	v_add_f32_e32 v66, 1.0, v66
	v_rcp_f32_e32 v66, v66
	s_nop 0
	v_mul_f32_e32 v65, v65, v66
	v_mul_f32_e32 v67, v64, v65
	v_cvt_pk_bf16_f32 v64, v81, v76
	v_cvt_pk_bf16_f32 v65, v74, v75
	v_cvt_pk_bf16_f32 v66, v72, v68
	v_cvt_pk_bf16_f32 v67, v69, v67
	v_mad_i64_i32 v[68:69], s[4:5], v80, s40, v[116:117]
	v_lshl_add_u64 v[68:69], v[68:69], 0, vcc
	v_lshl_add_u64 v[68:69], v[68:69], 0, s[86:87]
	v_lshl_add_u64 v[68:69], v[68:69], 0, v[128:129]
	global_store_dwordx4 v[68:69], v[64:67], off
	s_nop 1
	v_add_u32_e32 v64, 0x80, v146
	v_ashrrev_i32_e32 v65, 31, v64
	v_lshlrev_b64 v[66:67], 6, v[64:65]
	v_lshl_add_u64 v[78:79], s[2:3], 0, v[66:67]
	s_nop 0
	s_nop 0
	v_mov_b32_e32 v68, v56
	v_mov_b32_e32 v66, v208
	v_mov_b32_e32 v69, v60
	v_mov_b32_e32 v60, v57
	v_pk_mul_f32 v[68:69], v[68:69], v[66:67] op_sel_hi:[1,0]
	s_nop 0
	v_mul_f32_e32 v56, 0xbfb8aa3b, v69
	v_exp_f32_e32 v56, v56
	s_nop 0
	v_add_f32_e32 v56, 1.0, v56
	v_rcp_f32_e32 v56, v56
	s_nop 0
	v_mul_f32_e32 v56, v69, v56
	v_mul_f32_e32 v65, v68, v56
	v_pk_mul_f32 v[56:57], v[60:61], v[66:67] op_sel_hi:[1,0]
	s_nop 0
	v_mul_f32_e32 v60, 0xbfb8aa3b, v57
	v_exp_f32_e32 v60, v60
	s_nop 0
	v_add_f32_e32 v60, 1.0, v60
	v_rcp_f32_e32 v60, v60
	s_nop 0
	v_mul_f32_e32 v57, v57, v60
	v_mul_f32_e32 v60, v56, v57
	v_mov_b32_e32 v56, v58
	v_mov_b32_e32 v57, v62
	v_pk_mul_f32 v[56:57], v[56:57], v[66:67] op_sel_hi:[1,0]
	v_mov_b32_e32 v62, v59
	v_mul_f32_e32 v58, 0xbfb8aa3b, v57
	v_exp_f32_e32 v58, v58
	s_nop 0
	v_add_f32_e32 v58, 1.0, v58
	v_rcp_f32_e32 v58, v58
; __device__ __forceinline__ float sigmoidf_(float x) { return __builtin_amdgcn_rcpf(1.0f + __builtin_amdgcn_exp2f(-x * LOG2E)); }
; __device__ __forceinline__ unsigned cvt_pk_bf16(float lo, float hi) { unsigned r; asm volatile("v_cvt_pk_bf16_f32 %0, %1, %2" : "=v"(r) : "v"(lo), "v"(hi)); return r; }
;     __device__ __forceinline__ void operator()(const f32x4 (&acc)[2][2][4][2], const Unit& u, int wr, int wc, int fr, int fq) const {
;     ...
;         for (int ai = 0; ai < 2; ++ai)
; #pragma unroll
;             for (int m = 0; m < 4; ++m) {
;                 const int row = u.pm * BM + ai * HALF + wr * 64 + m * 16 + fr;
;                 const float rs = row_rs(ss, row);
;                 float a[8];
; #pragma unroll
;                 for (int n = 0; n < 2; ++n)
; #pragma unroll
;                     for (int j = 0; j < 4; ++j) { const float gt = rs * acc[ai][0][m][n][j], up = rs * acc[ai][1][m][n][j]; a[4 * n + j] = gt * sigmoidf_(gt) * up; }
;                 u32x4 w; w.x = cvt_pk_bf16(a[0], a[1]); w.y = cvt_pk_bf16(a[2], a[3]); w.z = cvt_pk_bf16(a[4], a[5]); w.w = cvt_pk_bf16(a[6], a[7]);
;                 *(u32x4*)(ACT + (size_t)row * DFF + u.pn * HALF + wc * 32 + fq * 8) = w;
	s_nop 0
	v_mul_f32_e32 v57, v57, v58
	v_mul_f32_e32 v58, v56, v57
	v_pk_mul_f32 v[56:57], v[62:63], v[66:67] op_sel_hi:[1,0]
	s_nop 0
	v_mul_f32_e32 v59, 0xbfb8aa3b, v57
	v_exp_f32_e32 v59, v59
	s_nop 0
	v_add_f32_e32 v59, 1.0, v59
	v_rcp_f32_e32 v59, v59
	s_nop 0
	v_mul_f32_e32 v57, v57, v59
	v_mul_f32_e32 v59, v56, v57
	v_mov_b32_e32 v56, v48
	v_mov_b32_e32 v57, v52
	v_pk_mul_f32 v[56:57], v[56:57], v[66:67] op_sel_hi:[1,0]
	v_mov_b32_e32 v52, v49
	v_mul_f32_e32 v48, 0xbfb8aa3b, v57
	v_exp_f32_e32 v48, v48
	s_nop 0
	v_add_f32_e32 v48, 1.0, v48
	v_rcp_f32_e32 v48, v48
	s_nop 0
	v_mul_f32_e32 v48, v57, v48
	v_mul_f32_e32 v56, v56, v48
	v_pk_mul_f32 v[48:49], v[52:53], v[66:67] op_sel_hi:[1,0]
	s_nop 0
	v_mul_f32_e32 v52, 0xbfb8aa3b, v49
	v_exp_f32_e32 v52, v52
	s_nop 0
	v_add_f32_e32 v52, 1.0, v52
	v_rcp_f32_e32 v52, v52
	s_nop 0
	v_mul_f32_e32 v49, v49, v52
	v_mul_f32_e32 v52, v48, v49
	v_mov_b32_e32 v48, v50
	v_mov_b32_e32 v49, v54
	v_pk_mul_f32 v[48:49], v[48:49], v[66:67] op_sel_hi:[1,0]
	v_mov_b32_e32 v54, v51
	v_mul_f32_e32 v50, 0xbfb8aa3b, v49
	v_exp_f32_e32 v50, v50
	s_nop 0
	v_add_f32_e32 v50, 1.0, v50
	v_rcp_f32_e32 v50, v50
	s_nop 0
	v_mul_f32_e32 v49, v49, v50
	v_mul_f32_e32 v53, v48, v49
	v_pk_mul_f32 v[48:49], v[54:55], v[66:67] op_sel_hi:[1,0]
	s_nop 0
	v_mul_f32_e32 v50, 0xbfb8aa3b, v49
	v_exp_f32_e32 v50, v50
	s_nop 0
	v_add_f32_e32 v50, 1.0, v50
	v_rcp_f32_e32 v50, v50
	s_nop 0
	v_mul_f32_e32 v49, v49, v50
	v_mul_f32_e32 v51, v48, v49
	v_cvt_pk_bf16_f32 v48, v65, v60
	v_cvt_pk_bf16_f32 v49, v58, v59
	v_cvt_pk_bf16_f32 v50, v56, v52
	v_cvt_pk_bf16_f32 v51, v53, v51
	v_mad_i64_i32 v[52:53], s[4:5], v64, s40, v[116:117]
	v_lshl_add_u64 v[52:53], v[52:53], 0, vcc
	v_lshl_add_u64 v[52:53], v[52:53], 0, s[86:87]
	v_lshl_add_u64 v[52:53], v[52:53], 0, v[128:129]
	global_store_dwordx4 v[52:53], v[48:51], off
	s_nop 1
	v_add_u32_e32 v48, 0x90, v146
	v_ashrrev_i32_e32 v49, 31, v48
	v_lshlrev_b64 v[50:51], 6, v[48:49]
	v_lshl_add_u64 v[62:63], s[2:3], 0, v[50:51]
	s_nop 0
	s_nop 0
	v_mov_b32_e32 v52, v40
	v_mov_b32_e32 v50, v209
	v_mov_b32_e32 v53, v44
	v_mov_b32_e32 v44, v41
	v_pk_mul_f32 v[52:53], v[52:53], v[50:51] op_sel_hi:[1,0]
	s_nop 0
	v_mul_f32_e32 v40, 0xbfb8aa3b, v53
	v_exp_f32_e32 v40, v40
	s_nop 0
	v_add_f32_e32 v40, 1.0, v40
	v_rcp_f32_e32 v40, v40
	s_nop 0
	v_mul_f32_e32 v40, v53, v40
	v_mul_f32_e32 v49, v52, v40
	v_pk_mul_f32 v[40:41], v[44:45], v[50:51] op_sel_hi:[1,0]
	s_nop 0
	v_mul_f32_e32 v44, 0xbfb8aa3b, v41
	v_exp_f32_e32 v44, v44
	s_nop 0
	v_add_f32_e32 v44, 1.0, v44
	v_rcp_f32_e32 v44, v44
	s_nop 0
	v_mul_f32_e32 v41, v41, v44
	v_mul_f32_e32 v44, v40, v41
	v_mov_b32_e32 v40, v42
	v_mov_b32_e32 v41, v46
	v_pk_mul_f32 v[40:41], v[40:41], v[50:51] op_sel_hi:[1,0]
	v_mov_b32_e32 v46, v43
	v_mul_f32_e32 v42, 0xbfb8aa3b, v41
	v_exp_f32_e32 v42, v42
	s_nop 0
	v_add_f32_e32 v42, 1.0, v42
	v_rcp_f32_e32 v42, v42
	s_nop 0
	v_mul_f32_e32 v41, v41, v42
	v_mul_f32_e32 v42, v40, v41
	v_pk_mul_f32 v[40:41], v[46:47], v[50:51] op_sel_hi:[1,0]
	s_nop 0
	v_mul_f32_e32 v43, 0xbfb8aa3b, v41
	v_exp_f32_e32 v43, v43
	s_nop 0
	v_add_f32_e32 v43, 1.0, v43
	v_rcp_f32_e32 v43, v43
	s_nop 0
	v_mul_f32_e32 v41, v41, v43
	v_mul_f32_e32 v43, v40, v41
	v_mov_b32_e32 v40, v32
	v_mov_b32_e32 v41, v36
	v_pk_mul_f32 v[40:41], v[40:41], v[50:51] op_sel_hi:[1,0]
	v_mov_b32_e32 v36, v33
	v_mul_f32_e32 v32, 0xbfb8aa3b, v41
	v_exp_f32_e32 v32, v32
	s_nop 0
	v_add_f32_e32 v32, 1.0, v32
	v_rcp_f32_e32 v32, v32
	s_nop 0
	v_mul_f32_e32 v32, v41, v32
	v_mul_f32_e32 v40, v40, v32
	v_pk_mul_f32 v[32:33], v[36:37], v[50:51] op_sel_hi:[1,0]
	s_nop 0
	v_mul_f32_e32 v36, 0xbfb8aa3b, v33
	v_exp_f32_e32 v36, v36
	s_nop 0
	v_add_f32_e32 v36, 1.0, v36
	v_rcp_f32_e32 v36, v36
	s_nop 0
	v_mul_f32_e32 v33, v33, v36
	v_mul_f32_e32 v36, v32, v33
	v_mov_b32_e32 v32, v34
	v_mov_b32_e32 v33, v38
	v_pk_mul_f32 v[32:33], v[32:33], v[50:51] op_sel_hi:[1,0]
	v_mov_b32_e32 v38, v35
	v_mul_f32_e32 v34, 0xbfb8aa3b, v33
	v_exp_f32_e32 v34, v34
	s_nop 0
	v_add_f32_e32 v34, 1.0, v34
	v_rcp_f32_e32 v34, v34
	s_nop 0
	v_mul_f32_e32 v33, v33, v34
	v_mul_f32_e32 v37, v32, v33
	v_pk_mul_f32 v[32:33], v[38:39], v[50:51] op_sel_hi:[1,0]
	s_nop 0
	v_mul_f32_e32 v34, 0xbfb8aa3b, v33
	v_exp_f32_e32 v34, v34
	s_nop 0
	v_add_f32_e32 v34, 1.0, v34
	v_rcp_f32_e32 v34, v34
	s_nop 0
	v_mul_f32_e32 v33, v33, v34
	v_mul_f32_e32 v35, v32, v33
	v_cvt_pk_bf16_f32 v32, v49, v44
	v_cvt_pk_bf16_f32 v33, v42, v43
	v_cvt_pk_bf16_f32 v34, v40, v36
	v_cvt_pk_bf16_f32 v35, v37, v35
	v_mad_i64_i32 v[36:37], s[4:5], v48, s40, v[116:117]
	v_lshl_add_u64 v[36:37], v[36:37], 0, vcc
	v_lshl_add_u64 v[36:37], v[36:37], 0, s[86:87]
	v_lshl_add_u64 v[36:37], v[36:37], 0, v[128:129]
	global_store_dwordx4 v[36:37], v[32:35], off
	s_nop 1
	v_add_u32_e32 v32, 0xa0, v146
	v_ashrrev_i32_e32 v33, 31, v32
	v_lshlrev_b64 v[34:35], 6, v[32:33]
	v_lshl_add_u64 v[46:47], s[2:3], 0, v[34:35]
	s_nop 0
	s_nop 0
	v_mov_b32_e32 v36, v24
	v_mov_b32_e32 v34, v210
	v_mov_b32_e32 v37, v28
	v_mov_b32_e32 v28, v25
	v_pk_mul_f32 v[36:37], v[36:37], v[34:35] op_sel_hi:[1,0]
	s_nop 0
	v_mul_f32_e32 v24, 0xbfb8aa3b, v37
	v_exp_f32_e32 v24, v24
	s_nop 0
	v_add_f32_e32 v24, 1.0, v24
	v_rcp_f32_e32 v24, v24
	s_nop 0
	v_mul_f32_e32 v24, v37, v24
	v_mul_f32_e32 v33, v36, v24
; __device__ __forceinline__ float sigmoidf_(float x) { return __builtin_amdgcn_rcpf(1.0f + __builtin_amdgcn_exp2f(-x * LOG2E)); }
; __device__ __forceinline__ unsigned cvt_pk_bf16(float lo, float hi) { unsigned r; asm volatile("v_cvt_pk_bf16_f32 %0, %1, %2" : "=v"(r) : "v"(lo), "v"(hi)); return r; }
; #define PG8_BAR __builtin_amdgcn_s_barrier()
;     __device__ __forceinline__ void operator()(const f32x4 (&acc)[2][2][4][2], const Unit& u, int wr, int wc, int fr, int fq) const {
;     ...
;         for (int ai = 0; ai < 2; ++ai)
; #pragma unroll
;             for (int m = 0; m < 4; ++m) {
;                 const int row = u.pm * BM + ai * HALF + wr * 64 + m * 16 + fr;
;                 const float rs = row_rs(ss, row);
;                 float a[8];
; #pragma unroll
;                 for (int n = 0; n < 2; ++n)
; #pragma unroll
;                     for (int j = 0; j < 4; ++j) { const float gt = rs * acc[ai][0][m][n][j], up = rs * acc[ai][1][m][n][j]; a[4 * n + j] = gt * sigmoidf_(gt) * up; }
;                 u32x4 w; w.x = cvt_pk_bf16(a[0], a[1]); w.y = cvt_pk_bf16(a[2], a[3]); w.z = cvt_pk_bf16(a[4], a[5]); w.w = cvt_pk_bf16(a[6], a[7]);
;                 *(u32x4*)(ACT + (size_t)row * DFF + u.pn * HALF + wc * 32 + fq * 8) = w;
; template <class Epi, class Sched, bool ALIGN_EPI = false, bool SP2 = false>
; __device__ __forceinline__ void gemm_phase(PG8_LAS unsigned char* lds, const Gemm g, const Sched& S, const Epi& E) {
;     ...
;         if constexpr (ALIGN_EPI) { if (wr == 0) PG8_BAR; }
;         if constexpr (!Epi::AFTER_DRAIN) { E(acc, cur, wr, wc, fr, fq); S.done(cur); }
;         if (!has_next) break;
	v_pk_mul_f32 v[24:25], v[28:29], v[34:35] op_sel_hi:[1,0]
	s_nop 0
	v_mul_f32_e32 v28, 0xbfb8aa3b, v25
	v_exp_f32_e32 v28, v28
	s_nop 0
	v_add_f32_e32 v28, 1.0, v28
	v_rcp_f32_e32 v28, v28
	s_nop 0
	v_mul_f32_e32 v25, v25, v28
	v_mul_f32_e32 v28, v24, v25
	v_mov_b32_e32 v24, v26
	v_mov_b32_e32 v25, v30
	v_pk_mul_f32 v[24:25], v[24:25], v[34:35] op_sel_hi:[1,0]
	v_mov_b32_e32 v30, v27
	v_mul_f32_e32 v26, 0xbfb8aa3b, v25
	v_exp_f32_e32 v26, v26
	s_nop 0
	v_add_f32_e32 v26, 1.0, v26
	v_rcp_f32_e32 v26, v26
	s_nop 0
	v_mul_f32_e32 v25, v25, v26
	v_mul_f32_e32 v26, v24, v25
	v_pk_mul_f32 v[24:25], v[30:31], v[34:35] op_sel_hi:[1,0]
	s_nop 0
	v_mul_f32_e32 v27, 0xbfb8aa3b, v25
	v_exp_f32_e32 v27, v27
	s_nop 0
	v_add_f32_e32 v27, 1.0, v27
	v_rcp_f32_e32 v27, v27
	s_nop 0
	v_mul_f32_e32 v25, v25, v27
	v_mul_f32_e32 v27, v24, v25
	v_mov_b32_e32 v24, v16
	v_mov_b32_e32 v25, v20
	v_pk_mul_f32 v[24:25], v[24:25], v[34:35] op_sel_hi:[1,0]
	v_mov_b32_e32 v20, v17
	v_mul_f32_e32 v16, 0xbfb8aa3b, v25
	v_exp_f32_e32 v16, v16
	s_nop 0
	v_add_f32_e32 v16, 1.0, v16
	v_rcp_f32_e32 v16, v16
	s_nop 0
	v_mul_f32_e32 v16, v25, v16
	v_mul_f32_e32 v24, v24, v16
	v_pk_mul_f32 v[16:17], v[20:21], v[34:35] op_sel_hi:[1,0]
	s_nop 0
	v_mul_f32_e32 v20, 0xbfb8aa3b, v17
	v_exp_f32_e32 v20, v20
	s_nop 0
	v_add_f32_e32 v20, 1.0, v20
	v_rcp_f32_e32 v20, v20
	s_nop 0
	v_mul_f32_e32 v17, v17, v20
	v_mul_f32_e32 v20, v16, v17
	v_mov_b32_e32 v16, v18
	v_mov_b32_e32 v17, v22
	v_pk_mul_f32 v[16:17], v[16:17], v[34:35] op_sel_hi:[1,0]
	v_mov_b32_e32 v22, v19
	v_mul_f32_e32 v18, 0xbfb8aa3b, v17
	v_exp_f32_e32 v18, v18
	s_nop 0
	v_add_f32_e32 v18, 1.0, v18
	v_rcp_f32_e32 v18, v18
	s_nop 0
	v_mul_f32_e32 v17, v17, v18
	v_mul_f32_e32 v21, v16, v17
	v_pk_mul_f32 v[16:17], v[22:23], v[34:35] op_sel_hi:[1,0]
	s_nop 0
	v_mul_f32_e32 v18, 0xbfb8aa3b, v17
	v_exp_f32_e32 v18, v18
	s_nop 0
	v_add_f32_e32 v18, 1.0, v18
	v_rcp_f32_e32 v18, v18
	s_nop 0
	v_mul_f32_e32 v17, v17, v18
	v_mul_f32_e32 v19, v16, v17
	v_cvt_pk_bf16_f32 v16, v33, v28
	v_cvt_pk_bf16_f32 v17, v26, v27
	v_cvt_pk_bf16_f32 v18, v24, v20
	v_cvt_pk_bf16_f32 v19, v21, v19
	v_mad_i64_i32 v[20:21], s[4:5], v32, s40, v[116:117]
	v_lshl_add_u64 v[20:21], v[20:21], 0, vcc
	v_lshl_add_u64 v[20:21], v[20:21], 0, s[86:87]
	v_lshl_add_u64 v[20:21], v[20:21], 0, v[128:129]
	global_store_dwordx4 v[20:21], v[16:19], off
	s_nop 1
	v_add_u32_e32 v16, 0xb0, v146
	v_ashrrev_i32_e32 v17, 31, v16
	v_lshlrev_b64 v[18:19], 6, v[16:17]
	v_lshl_add_u64 v[30:31], s[2:3], 0, v[18:19]
	s_nop 0
	s_nop 0
	v_mov_b32_e32 v20, v8
	v_mov_b32_e32 v18, v211
	v_mov_b32_e32 v21, v12
	v_mov_b32_e32 v12, v9
	v_pk_mul_f32 v[20:21], v[20:21], v[18:19] op_sel_hi:[1,0]
	s_nop 0
	v_mul_f32_e32 v8, 0xbfb8aa3b, v21
	v_exp_f32_e32 v8, v8
	s_nop 0
	v_add_f32_e32 v8, 1.0, v8
	v_rcp_f32_e32 v8, v8
	s_nop 0
	v_mul_f32_e32 v8, v21, v8
	v_mul_f32_e32 v17, v20, v8
	v_pk_mul_f32 v[8:9], v[12:13], v[18:19] op_sel_hi:[1,0]
	s_nop 0
	v_mul_f32_e32 v12, 0xbfb8aa3b, v9
	v_exp_f32_e32 v12, v12
	s_nop 0
	v_add_f32_e32 v12, 1.0, v12
	v_rcp_f32_e32 v12, v12
	s_nop 0
	v_mul_f32_e32 v9, v9, v12
	v_mul_f32_e32 v12, v8, v9
	v_mov_b32_e32 v8, v10
	v_mov_b32_e32 v9, v14
	v_pk_mul_f32 v[8:9], v[8:9], v[18:19] op_sel_hi:[1,0]
	v_mov_b32_e32 v14, v11
	v_mul_f32_e32 v10, 0xbfb8aa3b, v9
	v_exp_f32_e32 v10, v10
	s_nop 0
	v_add_f32_e32 v10, 1.0, v10
	v_rcp_f32_e32 v10, v10
	s_nop 0
	v_mul_f32_e32 v9, v9, v10
	v_mul_f32_e32 v10, v8, v9
	v_pk_mul_f32 v[8:9], v[14:15], v[18:19] op_sel_hi:[1,0]
	s_nop 0
	v_mul_f32_e32 v11, 0xbfb8aa3b, v9
	v_exp_f32_e32 v11, v11
	s_nop 0
	v_add_f32_e32 v11, 1.0, v11
	v_rcp_f32_e32 v11, v11
	s_nop 0
	v_mul_f32_e32 v9, v9, v11
	v_mul_f32_e32 v11, v8, v9
	v_mov_b32_e32 v8, v0
	v_mov_b32_e32 v9, v4
	v_pk_mul_f32 v[8:9], v[8:9], v[18:19] op_sel_hi:[1,0]
	v_mov_b32_e32 v4, v1
	v_mul_f32_e32 v0, 0xbfb8aa3b, v9
	v_exp_f32_e32 v0, v0
	s_nop 0
	v_add_f32_e32 v0, 1.0, v0
	v_rcp_f32_e32 v0, v0
	s_nop 0
	v_mul_f32_e32 v0, v9, v0
	v_mul_f32_e32 v8, v8, v0
	v_pk_mul_f32 v[0:1], v[4:5], v[18:19] op_sel_hi:[1,0]
	s_nop 0
	v_mul_f32_e32 v4, 0xbfb8aa3b, v1
	v_exp_f32_e32 v4, v4
	s_nop 0
	v_add_f32_e32 v4, 1.0, v4
	v_rcp_f32_e32 v4, v4
	s_nop 0
	v_mul_f32_e32 v1, v1, v4
	v_mul_f32_e32 v4, v0, v1
	v_mov_b32_e32 v0, v2
	v_mov_b32_e32 v1, v6
	v_pk_mul_f32 v[0:1], v[0:1], v[18:19] op_sel_hi:[1,0]
	v_mov_b32_e32 v6, v3
	v_mul_f32_e32 v2, 0xbfb8aa3b, v1
	v_exp_f32_e32 v2, v2
	s_nop 0
	v_add_f32_e32 v2, 1.0, v2
	v_rcp_f32_e32 v2, v2
	s_nop 0
	v_mul_f32_e32 v1, v1, v2
	v_mul_f32_e32 v5, v0, v1
	v_pk_mul_f32 v[0:1], v[6:7], v[18:19] op_sel_hi:[1,0]
	s_nop 0
	v_mul_f32_e32 v2, 0xbfb8aa3b, v1
	v_exp_f32_e32 v2, v2
	s_nop 0
	v_add_f32_e32 v2, 1.0, v2
	v_rcp_f32_e32 v2, v2
	s_nop 0
	v_mul_f32_e32 v1, v1, v2
	v_mul_f32_e32 v3, v0, v1
	v_cvt_pk_bf16_f32 v0, v17, v12
	v_cvt_pk_bf16_f32 v1, v10, v11
	v_cvt_pk_bf16_f32 v2, v8, v4
	v_cvt_pk_bf16_f32 v3, v5, v3
	v_mad_i64_i32 v[4:5], s[4:5], v16, s40, v[116:117]
	v_lshl_add_u64 v[4:5], v[4:5], 0, vcc
	v_lshl_add_u64 v[4:5], v[4:5], 0, s[86:87]
	v_lshl_add_u64 v[4:5], v[4:5], 0, v[128:129]
	s_mov_b64 s[4:5], -1
	s_andn2_b64 vcc, exec, s[38:39]
	global_store_dwordx4 v[4:5], v[0:3], off
	s_cbranch_vccnz .LBB0_1109
	s_andn2_b64 vcc, exec, s[90:91]
	s_cbranch_vccnz .LBB0_1108
	s_barrier
	s_branch .LBB0_1108
